# attention tile loop: static s_setprio 1 for waves 0-3 instead of waves 4-7 (per-half comparison)
# baseline (speedup 1.0000x reference)
.LBB0_562:
	v_mov_b32_e32 v41, v181
	s_add_i32 s7, 0, 0x14000
	v_ashrrev_i32_e32 v0, 6, v41
	v_and_b32_e32 v1, 0x3fffffc0, v41
	s_and_b32 s5, s5, 7
	v_and_b32_e32 v168, 31, v41
	v_lshl_add_u32 v169, v1, 2, s7
	s_movk_i32 s7, 0x1800
	v_lshl_add_u32 v170, v0, 5, s6
	v_mul_lo_u32 v37, v0, s7
	v_add_u32_e32 v36, v170, v168
	v_mov_b64_e32 v[0:1], s[60:61]
	s_mul_i32 s11, s5, 0xc0
	v_bfe_u32 v159, v41, 5, 1
	v_mad_i64_i32 v[0:1], s[6:7], v36, s87, v[0:1]
	s_lshl_b32 s44, s11, 1
	v_lshl_add_u64 v[0:1], v[0:1], 0, s[44:45]
	v_lshlrev_b32_e32 v176, 4, v159
	v_lshl_add_u64 v[4:5], v[0:1], 0, v[176:177]
	global_load_dwordx4 v[42:45], v[4:5], off
	global_load_dwordx4 v[46:49], v[4:5], off offset:32
	global_load_dwordx4 v[50:53], v[4:5], off offset:64
	global_load_dwordx4 v[32:35], v[4:5], off offset:96
	global_load_dwordx4 v[28:31], v[4:5], off offset:128
	global_load_dwordx4 v[24:27], v[4:5], off offset:160
	global_load_dwordx4 v[20:23], v[4:5], off offset:192
	global_load_dwordx4 v[16:19], v[4:5], off offset:224
	global_load_dwordx4 v[8:11], v[4:5], off offset:256
	global_load_dwordx4 v[12:15], v[4:5], off offset:288
	global_load_dwordx4 v[0:3], v[4:5], off offset:320
	s_nop 0
	global_load_dwordx4 v[4:7], v[4:5], off offset:352
	v_and_b32_e32 v66, 63, v41
	s_add_i32 s6, 0, 0x14800
	v_lshlrev_b32_e32 v67, 4, v66
	v_add_u32_e32 v37, s6, v37
	v_add_u32_e32 v171, v37, v67
	s_mov_b64 s[6:7], 0x40040
	v_ashrrev_i32_e32 v148, 4, v41
	s_cmp_lg_u32 0, -1
	s_cselect_b32 s16, 0, 0
	v_ashrrev_i32_e32 v149, 31, v148
	v_lshl_add_u64 v[156:157], v[148:149], 0, 32
	s_mov_b32 s46, s45
	s_mov_b32 s47, s45
	s_mov_b32 s48, s45
	s_mov_b32 s49, s45
	s_mov_b32 s50, s45
	s_mov_b32 s51, s45
	s_mov_b32 s52, s45
	s_mov_b32 s53, s45
	s_mov_b32 s54, s45
	s_mov_b32 s55, s45
	s_mov_b32 s56, s45
	s_mov_b32 s57, s45
	s_mov_b32 s58, s45
	s_mov_b32 s59, s45
	s_mov_b32 s13, 2
	v_lshl_add_u32 v173, v168, 2, v169
	v_mov_b32_e32 v188, 0
	s_waitcnt vmcnt(0)
	v_and_b32_e32 v68, 0xffff0000, v42
	v_and_b32_e32 v70, 0xffff0000, v43
	v_lshlrev_b32_e32 v69, 16, v42
	v_mul_f32_e32 v38, v68, v68
	v_lshlrev_b32_e32 v71, 16, v43
	v_mul_f32_e32 v39, v70, v70
	v_fmac_f32_e32 v38, v69, v69
	v_fmac_f32_e32 v39, v71, v71
	v_and_b32_e32 v72, 0xffff0000, v44
	v_add_f32_e32 v38, v38, v39
	v_lshlrev_b32_e32 v73, 16, v44
	v_mul_f32_e32 v39, v72, v72
	v_fmac_f32_e32 v39, v73, v73
	v_and_b32_e32 v76, 0xffff0000, v45
	v_add_f32_e32 v38, v39, v38
	v_lshlrev_b32_e32 v77, 16, v45
	v_mul_f32_e32 v39, v76, v76
	v_fmac_f32_e32 v39, v77, v77
	v_and_b32_e32 v74, 0xffff0000, v46
	v_add_f32_e32 v38, v39, v38
	v_lshlrev_b32_e32 v75, 16, v46
	v_mul_f32_e32 v39, v74, v74
	v_fmac_f32_e32 v39, v75, v75
	v_and_b32_e32 v78, 0xffff0000, v47
	v_add_f32_e32 v38, v39, v38
	v_lshlrev_b32_e32 v79, 16, v47
	v_mul_f32_e32 v39, v78, v78
	v_fmac_f32_e32 v39, v79, v79
	v_and_b32_e32 v80, 0xffff0000, v48
	v_add_f32_e32 v38, v39, v38
	v_lshlrev_b32_e32 v82, 16, v48
	v_mul_f32_e32 v39, v80, v80
	v_fmac_f32_e32 v39, v82, v82
	v_and_b32_e32 v85, 0xffff0000, v49
	v_add_f32_e32 v38, v39, v38
	v_lshlrev_b32_e32 v86, 16, v49
	v_mul_f32_e32 v39, v85, v85
	v_fmac_f32_e32 v39, v86, v86
	v_and_b32_e32 v83, 0xffff0000, v50
	v_add_f32_e32 v38, v39, v38
	v_lshlrev_b32_e32 v84, 16, v50
	v_mul_f32_e32 v39, v83, v83
	v_fmac_f32_e32 v39, v84, v84
	v_and_b32_e32 v87, 0xffff0000, v51
	v_add_f32_e32 v38, v39, v38
	v_lshlrev_b32_e32 v88, 16, v51
	v_mul_f32_e32 v39, v87, v87
	v_fmac_f32_e32 v39, v88, v88
	v_and_b32_e32 v93, 0xffff0000, v52
	v_add_f32_e32 v38, v39, v38
	v_lshlrev_b32_e32 v95, 16, v52
	v_mul_f32_e32 v39, v93, v93
	v_fmac_f32_e32 v39, v95, v95
	v_and_b32_e32 v104, 0xffff0000, v53
	v_add_f32_e32 v38, v39, v38
	v_lshlrev_b32_e32 v105, 16, v53
	v_mul_f32_e32 v39, v104, v104
	v_and_b32_e32 v91, 0xffff0000, v32
	v_fmac_f32_e32 v39, v105, v105
	v_lshlrev_b32_e32 v108, 16, v32
	v_mul_f32_e32 v32, v91, v91
	v_and_b32_e32 v89, 0xffff0000, v33
	v_add_f32_e32 v38, v39, v38
	v_fmac_f32_e32 v32, v108, v108
	v_lshlrev_b32_e32 v94, 16, v33
	v_mul_f32_e32 v33, v89, v89
	v_add_f32_e32 v32, v32, v38
	v_fmac_f32_e32 v33, v94, v94
	v_and_b32_e32 v110, 0xffff0000, v34
	v_add_f32_e32 v32, v33, v32
	v_lshlrev_b32_e32 v112, 16, v34
	v_mul_f32_e32 v33, v110, v110
	v_fmac_f32_e32 v33, v112, v112
	v_and_b32_e32 v109, 0xffff0000, v35
	v_add_f32_e32 v32, v33, v32
	v_lshlrev_b32_e32 v111, 16, v35
	v_mul_f32_e32 v33, v109, v109
	v_and_b32_e32 v114, 0xffff0000, v28
	v_fmac_f32_e32 v33, v111, v111
	v_lshlrev_b32_e32 v113, 16, v28
	v_mul_f32_e32 v28, v114, v114
	v_and_b32_e32 v130, 0xffff0000, v29
	v_add_f32_e32 v32, v33, v32
	v_fmac_f32_e32 v28, v113, v113
	v_lshlrev_b32_e32 v115, 16, v29
	v_mul_f32_e32 v29, v130, v130
	v_add_f32_e32 v28, v28, v32
	v_fmac_f32_e32 v29, v115, v115
	v_and_b32_e32 v132, 0xffff0000, v30
	v_add_f32_e32 v28, v29, v28
	v_lshlrev_b32_e32 v131, 16, v30
	v_mul_f32_e32 v29, v132, v132
	v_fmac_f32_e32 v29, v131, v131
	v_and_b32_e32 v134, 0xffff0000, v31
	v_add_f32_e32 v28, v29, v28
	v_lshlrev_b32_e32 v133, 16, v31
	v_mul_f32_e32 v29, v134, v134
	v_and_b32_e32 v126, 0xffff0000, v24
	v_fmac_f32_e32 v29, v133, v133
	v_lshlrev_b32_e32 v128, 16, v24
	v_mul_f32_e32 v24, v126, v126
	v_and_b32_e32 v116, 0xffff0000, v25
	v_add_f32_e32 v28, v29, v28
	v_fmac_f32_e32 v24, v128, v128
	v_lshlrev_b32_e32 v118, 16, v25
	v_mul_f32_e32 v25, v116, v116
	v_add_f32_e32 v24, v24, v28
	v_fmac_f32_e32 v25, v118, v118
	v_and_b32_e32 v127, 0xffff0000, v26
	v_add_f32_e32 v24, v25, v24
	v_lshlrev_b32_e32 v129, 16, v26
	v_mul_f32_e32 v25, v127, v127
	v_fmac_f32_e32 v25, v129, v129
	v_and_b32_e32 v117, 0xffff0000, v27
	v_add_f32_e32 v24, v25, v24
	v_lshlrev_b32_e32 v119, 16, v27
	v_mul_f32_e32 v25, v117, v117
	v_and_b32_e32 v122, 0xffff0000, v20
	v_fmac_f32_e32 v25, v119, v119
	v_lshlrev_b32_e32 v124, 16, v20
	v_mul_f32_e32 v20, v122, v122
	v_and_b32_e32 v90, 0xffff0000, v21
	v_add_f32_e32 v24, v25, v24
	v_fmac_f32_e32 v20, v124, v124
	v_lshlrev_b32_e32 v120, 16, v21
	v_mul_f32_e32 v21, v90, v90
	v_add_f32_e32 v20, v20, v24
	v_fmac_f32_e32 v21, v120, v120
	v_and_b32_e32 v123, 0xffff0000, v22
	v_add_f32_e32 v20, v21, v20
	v_lshlrev_b32_e32 v125, 16, v22
	v_mul_f32_e32 v21, v123, v123
	v_fmac_f32_e32 v21, v125, v125
	v_and_b32_e32 v92, 0xffff0000, v23
	v_add_f32_e32 v20, v21, v20
	v_lshlrev_b32_e32 v121, 16, v23
	v_mul_f32_e32 v21, v92, v92
	v_fmac_f32_e32 v21, v121, v121
	v_add_f32_e32 v21, v21, v20
	v_and_b32_e32 v20, 0xffff0000, v16
	v_lshlrev_b32_e32 v22, 16, v16
	v_mul_f32_e32 v16, v20, v20
	v_fmac_f32_e32 v16, v22, v22
	v_add_f32_e32 v23, v16, v21
	v_and_b32_e32 v16, 0xffff0000, v17
	v_lshlrev_b32_e32 v21, 16, v17
	v_mul_f32_e32 v17, v16, v16
	v_fmac_f32_e32 v17, v21, v21
	v_lshlrev_b32_e32 v81, 16, v18
	v_and_b32_e32 v18, 0xffff0000, v18
	v_add_f32_e32 v17, v17, v23
	v_mul_f32_e32 v23, v18, v18
	v_fmac_f32_e32 v23, v81, v81
	v_add_f32_e32 v24, v23, v17
	v_and_b32_e32 v17, 0xffff0000, v19
	v_lshlrev_b32_e32 v23, 16, v19
	v_mul_f32_e32 v19, v17, v17
	v_fmac_f32_e32 v19, v23, v23
	v_add_f32_e32 v19, v19, v24
	v_and_b32_e32 v24, 32, v41
	global_load_dwordx4 v[96:99], v24, s[0:1] offset:16
	global_load_dwordx4 v[100:103], v24, s[0:1]
	global_load_dwordx4 v[240:243], v24, s[0:1] offset:80
	global_load_dwordx4 v[244:247], v24, s[0:1] offset:64
	global_load_dwordx4 v[248:251], v24, s[0:1] offset:144
	global_load_dwordx4 v[220:223], v24, s[0:1] offset:128
	global_load_dwordx4 v[232:235], v24, s[0:1] offset:208
	global_load_dwordx4 v[236:239], v24, s[0:1] offset:192
	v_and_b32_e32 v63, 0xffff0000, v12
	v_and_b32_e32 v62, 0xffff0000, v8
	v_mov_b32_e32 v25, v177
	v_lshlrev_b32_e32 v60, 16, v9
	v_and_b32_e32 v59, 0xffff0000, v13
	v_and_b32_e32 v58, 0xffff0000, v9
	v_lshlrev_b32_e32 v65, 16, v12
	v_lshlrev_b32_e32 v64, 16, v8
	v_pk_mul_f32 v[8:9], v[62:63], v[62:63]
	v_lshl_add_u64 v[26:27], s[40:41], 0, v[24:25]
	v_lshlrev_b32_e32 v25, 7, v36
	v_lshlrev_b32_e32 v39, 16, v15
	v_and_b32_e32 v37, 0xffff0000, v15
	v_lshlrev_b32_e32 v51, 16, v14
	v_and_b32_e32 v49, 0xffff0000, v14
	v_and_b32_e32 v48, 0xffff0000, v10
	v_lshlrev_b32_e32 v61, 16, v13
	v_pk_mul_f32 v[14:15], v[58:59], v[58:59]
	v_pk_fma_f32 v[8:9], v[64:65], v[64:65], v[8:9]
	v_and_b32_e32 v28, 0x3ff80, v25
	v_mov_b32_e32 v29, v177
	v_lshlrev_b32_e32 v38, 16, v11
	v_and_b32_e32 v36, 0xffff0000, v11
	v_lshlrev_b32_e32 v50, 16, v10
	v_pk_mul_f32 v[10:11], v[48:49], v[48:49]
	v_pk_fma_f32 v[14:15], v[60:61], v[60:61], v[14:15]
	v_add_f32_e32 v8, v8, v19
	v_lshl_add_u64 v[28:29], v[26:27], 0, v[28:29]
	v_pk_mul_f32 v[26:27], v[36:37], v[36:37]
	v_pk_fma_f32 v[10:11], v[50:51], v[50:51], v[10:11]
	v_add_f32_e32 v8, v14, v8
	v_pk_fma_f32 v[26:27], v[38:39], v[38:39], v[26:27]
	v_add_f32_e32 v8, v10, v8
	v_add_f32_e32 v8, v26, v8
	v_add_f32_e32 v8, v9, v8
	v_add_f32_e32 v8, v15, v8
	v_add_f32_e32 v8, v11, v8
	v_and_b32_e32 v26, 0xffff0000, v3
	v_and_b32_e32 v32, 0xffff0000, v2
	v_add_f32_e32 v10, v27, v8
	v_lshlrev_b32_e32 v31, 16, v7
	v_lshlrev_b32_e32 v30, 16, v3
	v_and_b32_e32 v27, 0xffff0000, v7
	v_lshlrev_b32_e32 v35, 16, v6
	v_lshlrev_b32_e32 v34, 16, v2
	v_and_b32_e32 v33, 0xffff0000, v6
	v_mov_b32_e32 v6, v26
	v_mov_b32_e32 v7, v32
	v_mov_b32_e32 v2, v30
	v_mov_b32_e32 v3, v34
	v_pk_mul_f32 v[6:7], v[6:7], v[6:7]
	v_mov_b32_e32 v8, v27
	v_mov_b32_e32 v9, v33
	v_pk_fma_f32 v[2:3], v[2:3], v[2:3], v[6:7]
	v_mov_b32_e32 v6, v31
	v_mov_b32_e32 v7, v35
	v_pk_mul_f32 v[8:9], v[8:9], v[8:9]
	v_and_b32_e32 v43, 0xffff0000, v5
	v_lshlrev_b32_e32 v56, 16, v0
	v_and_b32_e32 v53, 0xffff0000, v4
	v_pk_fma_f32 v[6:7], v[6:7], v[6:7], v[8:9]
	v_lshlrev_b32_e32 v47, 16, v5
	v_lshlrev_b32_e32 v46, 16, v1
	v_lshlrev_b32_e32 v57, 16, v4
	v_and_b32_e32 v52, 0xffff0000, v0
	v_mul_f32_e32 v9, v56, v56
	v_mov_b32_e32 v4, v43
	v_mov_b32_e32 v5, v53
	v_and_b32_e32 v42, 0xffff0000, v1
	v_mul_f32_e32 v8, v46, v46
	v_fmac_f32_e32 v9, v52, v52
	v_mov_b32_e32 v0, v47
	v_mov_b32_e32 v1, v57
	v_pk_mul_f32 v[4:5], v[4:5], v[4:5]
	v_fmac_f32_e32 v8, v42, v42
	v_pk_fma_f32 v[0:1], v[0:1], v[0:1], v[4:5]
	v_add_f32_e32 v4, v9, v10
	v_add_f32_e32 v4, v8, v4
	v_add_f32_e32 v3, v3, v4
	v_add_f32_e32 v2, v2, v3
	v_add_f32_e32 v1, v1, v2
	v_add_f32_e32 v0, v0, v1
	v_add_f32_e32 v0, v7, v0
	v_add_f32_e32 v0, v6, v0
	v_mov_b32_e32 v1, v0
	s_nop 1
	v_permlane32_swap_b32_e32 v0, v1
	v_add_f32_e32 v0, v0, v1
	v_fmamk_f32 v0, v0, 0x3baaaaab, v216
	v_cmp_gt_f32_e32 vcc, s85, v0
	v_mul_f32_e32 v1, 0x4b800000, v0
	v_lshl_add_u64 v[54:55], v[28:29], 0, s[30:31]
	v_cndmask_b32_e32 v0, v0, v1, vcc
	v_rsq_f32_e32 v0, v0
	v_lshl_add_u64 v[44:45], v[28:29], 0, s[6:7]
	v_mul_f32_e32 v1, 0x45800000, v0
	v_cndmask_b32_e32 v0, v0, v1, vcc
	v_mul_f32_e32 v40, 0x3dd53b94, v0
	v_mul_f32_e32 v0, v40, v69
	v_mul_f32_e32 v1, v40, v73
	v_mul_f32_e32 v2, v40, v68
	v_mul_f32_e32 v3, v40, v72
	v_mul_f32_e32 v4, v40, v71
	v_mul_f32_e32 v5, v40, v77
	v_mul_f32_e32 v6, v40, v70
	v_mul_f32_e32 v7, v40, v76
	s_waitcnt vmcnt(0)
	v_mul_f32_e32 v0, v100, v0
	v_mul_f32_e32 v1, v96, v1
	v_mul_f32_e32 v2, v101, v2
	v_mul_f32_e32 v3, v97, v3
	v_mul_f32_e32 v4, v102, v4
	v_mul_f32_e32 v5, v98, v5
	v_mul_f32_e32 v6, v103, v6
	v_mul_f32_e32 v7, v99, v7
	v_cvt_pk_bf16_f32 v96, v0, v2
	v_cvt_pk_bf16_f32 v97, v4, v6
	v_cvt_pk_bf16_f32 v98, v1, v3
	v_cvt_pk_bf16_f32 v99, v5, v7
	s_nop 1
	v_mov_b32_e32 v0, v240
	v_mov_b32_e32 v1, v241
	v_mov_b32_e32 v2, v242
	v_mov_b32_e32 v3, v243
	v_mov_b32_e32 v4, v244
	v_mov_b32_e32 v5, v245
	v_mov_b32_e32 v6, v246
	v_mov_b32_e32 v7, v247
	global_load_dwordx4 v[240:243], v24, s[0:1] offset:272
	global_load_dwordx4 v[244:247], v24, s[0:1] offset:256
	v_mul_f32_e32 v8, v40, v75
	v_add_co_u32_e32 v76, vcc, s88, v28
	v_mul_f32_e32 v4, v4, v8
	v_mul_f32_e32 v8, v40, v82
	v_mul_f32_e32 v0, v0, v8
	v_mul_f32_e32 v8, v40, v74
	v_mul_f32_e32 v5, v5, v8
	v_mul_f32_e32 v8, v40, v80
	v_mul_f32_e32 v1, v1, v8
	v_mul_f32_e32 v8, v40, v79
	v_mul_f32_e32 v6, v6, v8
	v_mul_f32_e32 v8, v40, v86
	v_mul_f32_e32 v2, v2, v8
	v_mul_f32_e32 v8, v40, v78
	v_mul_f32_e32 v7, v7, v8
	v_mul_f32_e32 v8, v40, v85
	v_mul_f32_e32 v3, v3, v8
	v_cvt_pk_bf16_f32 v100, v4, v5
	v_cvt_pk_bf16_f32 v101, v6, v7
	v_cvt_pk_bf16_f32 v102, v0, v1
	v_cvt_pk_bf16_f32 v103, v2, v3
	s_nop 1
	v_mov_b32_e32 v0, v248
	v_mov_b32_e32 v1, v249
	v_mov_b32_e32 v2, v250
	v_mov_b32_e32 v3, v251
	v_mov_b32_e32 v4, v220
	v_mov_b32_e32 v5, v221
	v_mov_b32_e32 v6, v222
	v_mov_b32_e32 v7, v223
	global_load_dwordx4 v[248:251], v24, s[0:1] offset:336
	global_load_dwordx4 v[220:223], v24, s[0:1] offset:320
	v_mul_f32_e32 v8, v40, v84
	v_addc_co_u32_e32 v77, vcc, 0, v29, vcc
	v_mul_f32_e32 v4, v8, v4
	v_mul_f32_e32 v8, v40, v95
	v_mul_f32_e32 v0, v8, v0
	v_mul_f32_e32 v8, v40, v83
	v_mul_f32_e32 v5, v8, v5
	v_mul_f32_e32 v8, v40, v93
	v_mul_f32_e32 v1, v8, v1
	v_mul_f32_e32 v8, v40, v88
	v_mul_f32_e32 v6, v8, v6
	v_mul_f32_e32 v8, v40, v105
	v_mul_f32_e32 v2, v8, v2
	v_mul_f32_e32 v8, v40, v87
	v_mul_f32_e32 v7, v8, v7
	v_mul_f32_e32 v8, v40, v104
	v_mul_f32_e32 v3, v8, v3
	v_cvt_pk_bf16_f32 v104, v4, v5
	v_cvt_pk_bf16_f32 v105, v6, v7
	v_cvt_pk_bf16_f32 v106, v0, v1
	v_cvt_pk_bf16_f32 v107, v2, v3
	s_nop 1
	v_mov_b32_e32 v0, v232
	v_mov_b32_e32 v1, v233
	v_mov_b32_e32 v2, v234
	v_mov_b32_e32 v3, v235
	v_mov_b32_e32 v4, v236
	v_mov_b32_e32 v5, v237
	v_mov_b32_e32 v6, v238
	v_mov_b32_e32 v7, v239
	global_load_dwordx4 v[232:235], v24, s[0:1] offset:400
	global_load_dwordx4 v[236:239], v24, s[0:1] offset:384
	v_mul_f32_e32 v8, v40, v108
	v_mul_f32_e32 v4, v8, v4
	v_mul_f32_e32 v8, v40, v112
	v_mul_f32_e32 v0, v8, v0
	v_mul_f32_e32 v8, v40, v91
	v_mul_f32_e32 v5, v8, v5
	v_mul_f32_e32 v8, v40, v110
	v_mul_f32_e32 v1, v8, v1
	v_mul_f32_e32 v8, v40, v94
	v_mul_f32_e32 v6, v8, v6
	v_mul_f32_e32 v8, v40, v111
	v_mul_f32_e32 v2, v8, v2
	v_mul_f32_e32 v8, v40, v89
	v_mul_f32_e32 v7, v8, v7
	v_mul_f32_e32 v8, v40, v109
	v_mul_f32_e32 v3, v8, v3
	v_cvt_pk_bf16_f32 v108, v4, v5
	v_cvt_pk_bf16_f32 v109, v6, v7
	v_cvt_pk_bf16_f32 v110, v0, v1
	v_cvt_pk_bf16_f32 v111, v2, v3
	s_waitcnt vmcnt(4)
	s_nop 1
	v_mov_b32_e32 v0, v240
	v_mov_b32_e32 v1, v241
	v_mov_b32_e32 v2, v242
	v_mov_b32_e32 v3, v243
	v_mov_b32_e32 v4, v244
	v_mov_b32_e32 v5, v245
	v_mov_b32_e32 v6, v246
	v_mov_b32_e32 v7, v247
	global_load_dwordx4 v[240:243], v24, s[0:1] offset:464
	global_load_dwordx4 v[244:247], v24, s[0:1] offset:448
	v_mul_f32_e32 v8, v40, v113
	v_mul_f32_e32 v4, v8, v4
	v_mul_f32_e32 v8, v40, v131
	v_mul_f32_e32 v0, v8, v0
	v_mul_f32_e32 v8, v40, v114
	v_mul_f32_e32 v5, v8, v5
	v_mul_f32_e32 v8, v40, v132
	v_mul_f32_e32 v1, v8, v1
	v_mul_f32_e32 v8, v40, v115
	v_mul_f32_e32 v6, v8, v6
	v_mul_f32_e32 v8, v40, v133
	v_mul_f32_e32 v2, v8, v2
	v_mul_f32_e32 v8, v40, v130
	v_mul_f32_e32 v7, v8, v7
	v_mul_f32_e32 v8, v40, v134
	v_mul_f32_e32 v3, v8, v3
	v_cvt_pk_bf16_f32 v112, v4, v5
	v_cvt_pk_bf16_f32 v113, v6, v7
	v_cvt_pk_bf16_f32 v114, v0, v1
	v_cvt_pk_bf16_f32 v115, v2, v3
	s_waitcnt vmcnt(4)
	s_nop 1
	v_mov_b32_e32 v0, v248
	v_mov_b32_e32 v1, v249
	v_mov_b32_e32 v2, v250
	v_mov_b32_e32 v3, v251
	v_mov_b32_e32 v4, v220
	v_mov_b32_e32 v5, v221
	v_mov_b32_e32 v6, v222
	v_mov_b32_e32 v7, v223
	v_mul_f32_e32 v8, v40, v128
	v_mul_f32_e32 v4, v8, v4
	v_mul_f32_e32 v8, v40, v129
	v_mul_f32_e32 v0, v8, v0
	v_mul_f32_e32 v8, v40, v126
	v_mul_f32_e32 v5, v8, v5
	v_mul_f32_e32 v8, v40, v127
	v_mul_f32_e32 v1, v8, v1
	v_mul_f32_e32 v8, v40, v118
	v_mul_f32_e32 v6, v8, v6
	v_mul_f32_e32 v8, v40, v119
	v_mul_f32_e32 v2, v8, v2
	v_mul_f32_e32 v8, v40, v116
	v_mul_f32_e32 v7, v8, v7
	v_mul_f32_e32 v8, v40, v117
	v_mul_f32_e32 v3, v8, v3
	v_cvt_pk_bf16_f32 v116, v4, v5
	v_cvt_pk_bf16_f32 v117, v6, v7
	v_cvt_pk_bf16_f32 v118, v0, v1
	v_cvt_pk_bf16_f32 v119, v2, v3
	s_waitcnt vmcnt(2)
	s_nop 1
	v_mov_b32_e32 v0, v232
	v_mov_b32_e32 v1, v233
	v_mov_b32_e32 v2, v234
	v_mov_b32_e32 v3, v235
	v_mov_b32_e32 v4, v236
	v_mov_b32_e32 v5, v237
	v_mov_b32_e32 v6, v238
	v_mov_b32_e32 v7, v239
	v_mul_f32_e32 v8, v40, v124
	v_mul_f32_e32 v4, v8, v4
	v_mul_f32_e32 v8, v40, v125
	v_mul_f32_e32 v8, v8, v0
	v_mul_f32_e32 v0, v40, v122
	v_mul_f32_e32 v0, v0, v5
	v_mul_f32_e32 v5, v40, v123
	v_mul_f32_e32 v5, v5, v1
	v_mul_f32_e32 v1, v40, v120
	v_mul_f32_e32 v1, v1, v6
	v_mul_f32_e32 v6, v40, v121
	v_mul_f32_e32 v6, v6, v2
	v_mul_f32_e32 v2, v40, v90
	v_mul_f32_e32 v2, v2, v7
	v_mul_f32_e32 v7, v40, v92
	v_mul_f32_e32 v3, v7, v3
	v_cvt_pk_bf16_f32 v0, v4, v0
	v_cvt_pk_bf16_f32 v1, v1, v2
	v_cvt_pk_bf16_f32 v2, v8, v5
	v_cvt_pk_bf16_f32 v3, v6, v3
	ds_write_b128 v171, v[0:3]
	s_waitcnt vmcnt(0)
	s_nop 1
	v_mov_b32_e32 v0, v240
	v_mov_b32_e32 v1, v241
	v_mov_b32_e32 v2, v242
	v_mov_b32_e32 v3, v243
	v_mov_b32_e32 v4, v244
	v_mov_b32_e32 v5, v245
	v_mov_b32_e32 v6, v246
	v_mov_b32_e32 v7, v247
	v_mul_f32_e32 v8, v40, v22
	v_mul_f32_e32 v4, v8, v4
	v_mul_f32_e32 v8, v40, v81
	v_mul_f32_e32 v8, v8, v0
	v_mul_f32_e32 v0, v40, v20
	v_mul_f32_e32 v0, v0, v5
	v_mul_f32_e32 v5, v40, v18
	v_mul_f32_e32 v5, v5, v1
	v_mul_f32_e32 v1, v40, v21
	v_mul_f32_e32 v1, v1, v6
	v_mul_f32_e32 v6, v40, v23
	v_mul_f32_e32 v6, v6, v2
	v_mul_f32_e32 v2, v40, v16
	v_mul_f32_e32 v2, v2, v7
	v_mul_f32_e32 v7, v40, v17
	v_mul_f32_e32 v3, v7, v3
	v_cvt_pk_bf16_f32 v0, v4, v0
	v_cvt_pk_bf16_f32 v1, v1, v2
	v_cvt_pk_bf16_f32 v2, v8, v5
	v_cvt_pk_bf16_f32 v3, v6, v3
	ds_write_b128 v171, v[0:3] offset:1024
	global_load_dwordx4 v[4:7], v24, s[0:1] offset:528
	global_load_dwordx4 v[16:19], v24, s[0:1] offset:512
	global_load_dwordx4 v[8:11], v24, s[0:1] offset:592
	global_load_dwordx4 v[20:23], v24, s[0:1] offset:576
	global_load_dwordx4 v[0:3], v[28:29], off offset:16
	global_load_dwordx4 v[12:15], v[28:29], off
	global_load_dwordx4 v[68:71], v[76:77], off
	global_load_dwordx4 v[72:75], v[54:55], off offset:16
	v_pk_mul_f32 v[54:55], v[40:41], v[64:65] op_sel_hi:[0,1]
	s_waitcnt vmcnt(6)
	v_mov_b32_e32 v64, v16
	s_waitcnt vmcnt(4)
	v_mov_b32_e32 v65, v20
	v_pk_mul_f32 v[54:55], v[54:55], v[64:65]
	s_waitcnt vmcnt(2)
	v_mov_b32_e32 v64, v12
	s_waitcnt vmcnt(1)
	v_mov_b32_e32 v65, v68
	v_pk_mul_f32 v[64:65], v[54:55], v[64:65]
	v_mov_b32_e32 v20, v17
	v_sub_f32_e32 v16, v64, v65
	v_mov_b32_e32 v64, v68
	v_mov_b32_e32 v65, v12
	v_pk_mul_f32 v[64:65], v[54:55], v[64:65]
	v_cndmask_b32_e64 v25, v54, v16, s[2:3]
	v_add_f32_e32 v12, v65, v64
	v_cndmask_b32_e64 v64, v55, v12, s[2:3]
	v_pk_mul_f32 v[54:55], v[40:41], v[62:63] op_sel_hi:[0,1]
	v_pk_mul_f32 v[16:17], v[54:55], v[20:21]
	v_mov_b32_e32 v68, v13
	v_pk_mul_f32 v[20:21], v[16:17], v[68:69]
	v_or_b32_e32 v65, 32, v176
	v_sub_f32_e32 v12, v20, v21
	v_cndmask_b32_e64 v20, v16, v12, s[2:3]
	v_mov_b32_e32 v12, v69
	v_pk_mul_f32 v[12:13], v[16:17], v[12:13]
	v_mov_b32_e32 v16, v18
	v_add_f32_e32 v12, v13, v12
	v_cndmask_b32_e64 v21, v17, v12, s[2:3]
	v_pk_mul_f32 v[12:13], v[40:41], v[60:61] op_sel_hi:[0,1]
	v_mov_b32_e32 v17, v22
	v_pk_mul_f32 v[12:13], v[12:13], v[16:17]
	v_mov_b32_e32 v16, v14
	v_mov_b32_e32 v17, v70
	v_pk_mul_f32 v[16:17], v[12:13], v[16:17]
	v_mov_b32_e32 v22, v19
	v_sub_f32_e32 v16, v16, v17
	v_cndmask_b32_e64 v18, v12, v16, s[2:3]
	v_mov_b32_e32 v16, v70
	v_mov_b32_e32 v17, v14
	v_pk_mul_f32 v[16:17], v[12:13], v[16:17]
	v_mov_b32_e32 v70, v15
	v_add_f32_e32 v12, v17, v16
	v_cndmask_b32_e64 v54, v13, v12, s[2:3]
	v_pk_mul_f32 v[12:13], v[40:41], v[58:59] op_sel_hi:[0,1]
	v_pk_mul_f32 v[12:13], v[12:13], v[22:23]
	v_mul_u32_u24_e32 v59, 0x180, v168
	v_pk_mul_f32 v[16:17], v[12:13], v[70:71]
	s_nop 0
	v_sub_f32_e32 v14, v16, v17
	v_cndmask_b32_e64 v16, v12, v14, s[2:3]
	v_mov_b32_e32 v14, v71
	v_pk_mul_f32 v[14:15], v[12:13], v[14:15]
	s_nop 0
	v_add_f32_e32 v12, v15, v14
	v_cndmask_b32_e64 v17, v13, v12, s[2:3]
	v_pk_mul_f32 v[12:13], v[40:41], v[50:51] op_sel_hi:[0,1]
	v_mov_b32_e32 v14, v4
	v_mov_b32_e32 v15, v8
	v_pk_mul_f32 v[12:13], v[12:13], v[14:15]
	v_mov_b32_e32 v14, v0
	s_waitcnt vmcnt(0)
	v_mov_b32_e32 v15, v72
	v_pk_mul_f32 v[14:15], v[12:13], v[14:15]
	v_mov_b32_e32 v8, v5
	v_sub_f32_e32 v4, v14, v15
	v_mov_b32_e32 v14, v72
	v_mov_b32_e32 v15, v0
	v_pk_mul_f32 v[14:15], v[12:13], v[14:15]
	v_cndmask_b32_e64 v19, v12, v4, s[2:3]
	v_add_f32_e32 v0, v15, v14
	v_cndmask_b32_e64 v14, v13, v0, s[2:3]
	v_pk_mul_f32 v[12:13], v[40:41], v[48:49] op_sel_hi:[0,1]
	v_pk_mul_f32 v[4:5], v[12:13], v[8:9]
	v_mov_b32_e32 v72, v1
	v_pk_mul_f32 v[8:9], v[4:5], v[72:73]
	s_nop 0
	v_sub_f32_e32 v0, v8, v9
	v_cndmask_b32_e64 v8, v4, v0, s[2:3]
	v_mov_b32_e32 v0, v73
	v_pk_mul_f32 v[0:1], v[4:5], v[0:1]
	v_mov_b32_e32 v4, v6
	v_add_f32_e32 v0, v1, v0
	v_cndmask_b32_e64 v9, v5, v0, s[2:3]
	v_pk_mul_f32 v[0:1], v[40:41], v[38:39] op_sel_hi:[0,1]
	v_mov_b32_e32 v5, v10
	v_pk_mul_f32 v[0:1], v[0:1], v[4:5]
	v_mov_b32_e32 v4, v2
	v_mov_b32_e32 v5, v74
	v_pk_mul_f32 v[4:5], v[0:1], v[4:5]
	v_mov_b32_e32 v10, v7
	v_sub_f32_e32 v4, v4, v5
	v_cndmask_b32_e64 v6, v0, v4, s[2:3]
	v_mov_b32_e32 v4, v74
	v_mov_b32_e32 v5, v2
	v_pk_mul_f32 v[4:5], v[0:1], v[4:5]
	v_mov_b32_e32 v74, v3
	v_add_f32_e32 v0, v5, v4
	v_cndmask_b32_e64 v12, v1, v0, s[2:3]
	v_pk_mul_f32 v[0:1], v[40:41], v[36:37] op_sel_hi:[0,1]
	v_pk_mul_f32 v[0:1], v[0:1], v[10:11]
	s_nop 0
	v_pk_mul_f32 v[4:5], v[0:1], v[74:75]
	s_nop 0
	v_sub_f32_e32 v2, v4, v5
	v_cndmask_b32_e64 v4, v0, v2, s[2:3]
	v_mov_b32_e32 v2, v75
	v_pk_mul_f32 v[2:3], v[0:1], v[2:3]
	s_nop 0
	v_add_f32_e32 v0, v3, v2
	v_cndmask_b32_e64 v5, v1, v0, s[2:3]
	v_cvt_pk_bf16_f32 v0, v25, v20
	v_cvt_pk_bf16_f32 v1, v18, v16
	v_cvt_pk_bf16_f32 v2, v19, v8
	v_cvt_pk_bf16_f32 v3, v6, v4
	ds_write_b128 v171, v[0:3] offset:2048
	v_cvt_pk_bf16_f32 v0, v64, v21
	v_cvt_pk_bf16_f32 v1, v54, v17
	v_cvt_pk_bf16_f32 v2, v14, v9
	v_cvt_pk_bf16_f32 v3, v12, v5
	ds_write_b128 v171, v[0:3] offset:3072
	global_load_dwordx4 v[0:3], v24, s[0:1] offset:656
	global_load_dwordx4 v[4:7], v24, s[0:1] offset:640
	global_load_dwordx4 v[8:11], v24, s[0:1] offset:720
	global_load_dwordx4 v[12:15], v24, s[0:1] offset:704
	global_load_dwordx4 v[16:19], v[28:29], off offset:80
	global_load_dwordx4 v[20:23], v[28:29], off offset:64
	global_load_dwordx4 v[36:39], v[76:77], off offset:64
	global_load_dwordx4 v[48:51], v[44:45], off offset:16
	v_pk_mul_f32 v[24:25], v[40:41], v[56:57] op_sel_hi:[0,1]
	s_waitcnt vmcnt(6)
	v_mov_b32_e32 v28, v4
	s_waitcnt vmcnt(4)
	v_mov_b32_e32 v29, v12
	v_pk_mul_f32 v[24:25], v[24:25], v[28:29]
	s_waitcnt vmcnt(2)
	v_mov_b32_e32 v28, v20
	s_waitcnt vmcnt(1)
	v_mov_b32_e32 v29, v36
	v_pk_mul_f32 v[28:29], v[24:25], v[28:29]
	v_mov_b32_e32 v12, v5
	v_sub_f32_e32 v4, v28, v29
	v_mov_b32_e32 v28, v36
	v_mov_b32_e32 v29, v20
	v_pk_mul_f32 v[28:29], v[24:25], v[28:29]
	v_cndmask_b32_e64 v44, v24, v4, s[2:3]
	v_add_f32_e32 v4, v29, v28
	v_cndmask_b32_e64 v28, v25, v4, s[2:3]
	v_pk_mul_f32 v[24:25], v[40:41], v[52:53] op_sel_hi:[0,1]
	v_pk_mul_f32 v[4:5], v[24:25], v[12:13]
	v_mov_b32_e32 v36, v21
	v_pk_mul_f32 v[12:13], v[4:5], v[36:37]
	v_mov_b32_e32 v20, v37
	v_sub_f32_e32 v12, v12, v13
	v_cndmask_b32_e64 v24, v4, v12, s[2:3]
	v_pk_mul_f32 v[12:13], v[4:5], v[20:21]
	s_nop 0
	v_add_f32_e32 v4, v13, v12
	v_cndmask_b32_e64 v20, v5, v4, s[2:3]
	v_pk_mul_f32 v[4:5], v[40:41], v[46:47] op_sel_hi:[0,1]
	v_mov_b32_e32 v12, v6
	v_mov_b32_e32 v13, v14
	v_pk_mul_f32 v[4:5], v[4:5], v[12:13]
	v_mov_b32_e32 v12, v22
	v_mov_b32_e32 v13, v38
	v_pk_mul_f32 v[12:13], v[4:5], v[12:13]
	v_mov_b32_e32 v14, v7
	v_sub_f32_e32 v6, v12, v13
	v_mov_b32_e32 v12, v38
	v_mov_b32_e32 v13, v22
	v_pk_mul_f32 v[12:13], v[4:5], v[12:13]
	v_cndmask_b32_e64 v21, v4, v6, s[2:3]
	v_add_f32_e32 v4, v13, v12
	v_cndmask_b32_e64 v12, v5, v4, s[2:3]
	v_pk_mul_f32 v[4:5], v[40:41], v[42:43] op_sel_hi:[0,1]
	v_pk_mul_f32 v[4:5], v[4:5], v[14:15]
	v_mov_b32_e32 v38, v23
	v_pk_mul_f32 v[6:7], v[4:5], v[38:39]
	v_mov_b32_e32 v22, v39
	v_sub_f32_e32 v6, v6, v7
	v_cndmask_b32_e64 v13, v4, v6, s[2:3]
	v_pk_mul_f32 v[6:7], v[4:5], v[22:23]
	s_nop 0
	v_add_f32_e32 v4, v7, v6
	v_cndmask_b32_e64 v14, v5, v4, s[2:3]
	v_pk_mul_f32 v[4:5], v[40:41], v[34:35] op_sel_hi:[0,1]
	v_mov_b32_e32 v6, v0
	v_mov_b32_e32 v7, v8
	v_pk_mul_f32 v[4:5], v[4:5], v[6:7]
	v_mov_b32_e32 v6, v16
	s_waitcnt vmcnt(0)
	v_mov_b32_e32 v7, v48
	v_pk_mul_f32 v[6:7], v[4:5], v[6:7]
	v_mov_b32_e32 v8, v1
	v_sub_f32_e32 v0, v6, v7
	v_mov_b32_e32 v6, v48
	v_mov_b32_e32 v7, v16
	v_pk_mul_f32 v[6:7], v[4:5], v[6:7]
	v_cndmask_b32_e64 v15, v4, v0, s[2:3]
	v_add_f32_e32 v0, v7, v6
	v_cndmask_b32_e64 v6, v5, v0, s[2:3]
	v_pk_mul_f32 v[4:5], v[40:41], v[32:33] op_sel_hi:[0,1]
	v_pk_mul_f32 v[0:1], v[4:5], v[8:9]
	v_mov_b32_e32 v48, v17
	v_pk_mul_f32 v[4:5], v[0:1], v[48:49]
	v_mov_b32_e32 v16, v49
	v_sub_f32_e32 v4, v4, v5
	v_cndmask_b32_e64 v7, v0, v4, s[2:3]
	v_pk_mul_f32 v[4:5], v[0:1], v[16:17]
	v_mov_b32_e32 v49, v177
	v_add_f32_e32 v0, v5, v4
	v_cndmask_b32_e64 v8, v1, v0, s[2:3]
	v_pk_mul_f32 v[0:1], v[40:41], v[30:31] op_sel_hi:[0,1]
	v_mov_b32_e32 v4, v2
	v_mov_b32_e32 v5, v10
	v_pk_mul_f32 v[0:1], v[0:1], v[4:5]
	v_mov_b32_e32 v4, v18
	v_mov_b32_e32 v5, v50
	v_pk_mul_f32 v[4:5], v[0:1], v[4:5]
	v_mov_b32_e32 v10, v3
	v_sub_f32_e32 v2, v4, v5
	v_mov_b32_e32 v4, v50
	v_mov_b32_e32 v5, v18
	v_pk_mul_f32 v[4:5], v[0:1], v[4:5]
	v_cndmask_b32_e64 v9, v0, v2, s[2:3]
	v_add_f32_e32 v0, v5, v4
	v_cndmask_b32_e64 v4, v1, v0, s[2:3]
	v_pk_mul_f32 v[0:1], v[40:41], v[26:27] op_sel_hi:[0,1]
	v_pk_mul_f32 v[0:1], v[0:1], v[10:11]
	v_mov_b32_e32 v50, v19
	v_pk_mul_f32 v[2:3], v[0:1], v[50:51]
	v_mov_b32_e32 v18, v51
	v_sub_f32_e32 v2, v2, v3
	v_cndmask_b32_e64 v5, v0, v2, s[2:3]
	v_pk_mul_f32 v[2:3], v[0:1], v[18:19]
	v_lshlrev_b32_e32 v18, 4, v41
	v_add_f32_e32 v0, v3, v2
	v_cndmask_b32_e64 v10, v1, v0, s[2:3]
	v_cvt_pk_bf16_f32 v0, v44, v24
	v_cvt_pk_bf16_f32 v1, v21, v13
	v_cvt_pk_bf16_f32 v2, v15, v7
	v_cvt_pk_bf16_f32 v3, v9, v5
	ds_write_b128 v171, v[0:3] offset:4096
	v_cvt_pk_bf16_f32 v0, v28, v20
	v_cvt_pk_bf16_f32 v1, v12, v14
	v_cvt_pk_bf16_f32 v2, v6, v8
	v_cvt_pk_bf16_f32 v3, v4, v10
	ds_write_b128 v171, v[0:3] offset:5120
	v_and_b32_e32 v1, 0xfffff0, v148
	v_lshlrev_b32_e32 v3, 1, v148
	v_lshlrev_b32_e32 v0, 3, v41
	v_and_or_b32 v1, v3, 8, v1
	v_and_b32_e32 v2, 0x78, v0
	v_lshrrev_b32_e32 v3, 1, v148
	v_lshrrev_b32_e32 v1, 1, v1
	v_bfe_u32 v0, v0, 5, 2
	v_and_b32_e32 v4, 3, v148
	v_or_b32_e32 v1, v1, v0
	v_and_or_b32 v3, v3, 4, v4
	v_lshlrev_b32_e32 v1, 9, v1
	v_lshlrev_b32_e32 v3, 6, v3
	v_and_b32_e32 v4, 48, v18
	v_or3_b32 v19, v1, v3, v4
	v_add_u32_e32 v1, 32, v148
	v_and_b32_e32 v5, 0xfffff0, v1
	v_lshlrev_b32_e32 v1, 1, v1
	v_and_or_b32 v1, v1, 8, v5
	v_lshrrev_b32_e32 v1, 1, v1
	v_or_b32_e32 v0, v1, v0
	v_lshlrev_b32_e32 v0, 9, v0
	s_mov_b32 s2, 0x2aaaaaab
	v_or3_b32 v20, v0, v3, v4
	v_mul_hi_i32 v0, v41, s2
	v_lshrrev_b32_e32 v1, 31, v0
	v_ashrrev_i32_e32 v0, 2, v0
	v_add_u32_e32 v150, v0, v1
	v_add_u32_e32 v1, 0x200, v41
	v_mul_hi_i32 v3, v1, s2
	v_lshrrev_b32_e32 v4, 31, v3
	v_ashrrev_i32_e32 v3, 2, v3
	v_add_u32_e32 v152, v3, v4
	v_mul_lo_u32 v3, v152, 24
	v_sub_u32_e32 v1, v1, v3
	v_add_u32_e32 v3, 0x400, v41
	v_mul_hi_i32 v4, v3, s2
	v_lshrrev_b32_e32 v5, 31, v4
	v_ashrrev_i32_e32 v4, 2, v4
	v_mul_lo_u32 v0, v150, 24
	v_add_u32_e32 v154, v4, v5
	s_add_u32 s2, s94, s44
	v_sub_u32_e32 v0, v41, v0
	v_mul_lo_u32 v4, v154, 24
	s_addc_u32 s3, s95, 0
	s_lshl_b32 s5, s5, 8
	v_lshlrev_b32_e32 v8, 3, v0
	v_sub_u32_e32 v3, v3, v4
	v_mul_lo_u32 v4, v150, s89
	v_bitop3_b32 v0, v150, v0, 7 bitop3:0x6c
	s_add_u32 s6, s38, s5
	v_lshlrev_b32_e32 v12, 3, v1
	v_lshl_add_u32 v21, v0, 4, v4
	v_mul_lo_u32 v0, v152, s89
	v_bitop3_b32 v1, v152, v1, 7 bitop3:0x6c
	s_addc_u32 s7, s39, 0
	s_ashr_i32 s5, s4, 31
	v_ashrrev_i32_e32 v151, 31, v150
	v_lshl_add_u32 v22, v1, 4, v0
	v_mul_lo_u32 v0, v154, s89
	v_bitop3_b32 v1, v154, v3, 7 bitop3:0x6c
	v_lshl_add_u64 v[10:11], v[150:151], 0, s[4:5]
	v_mov_b64_e32 v[52:53], s[2:3]
	v_lshlrev_b32_e32 v16, 3, v3
	v_lshl_add_u32 v23, v1, 4, v0
	v_lshlrev_b32_e32 v0, 3, v66
	v_and_b32_e32 v1, 0xc0, v67
	v_lshlrev_b32_e32 v3, 1, v41
	v_ashrrev_i32_e32 v9, 31, v8
	v_mad_u64_u32 v[14:15], s[18:19], v10, s87, v[52:53]
	v_and_or_b32 v1, v0, 24, v1
	v_and_b32_e32 v3, 32, v3
	v_and_b32_e32 v0, 0x100, v0
	v_mad_i32_i24 v15, v11, s87, v15
	v_lshlrev_b64 v[50:51], 1, v[8:9]
	v_ashrrev_i32_e32 v153, 31, v152
	v_or3_b32 v58, v1, v3, v0
	v_lshl_add_u64 v[0:1], v[148:149], 0, s[4:5]
	v_lshl_add_u64 v[8:9], v[14:15], 0, v[50:51]
	v_lshl_add_u64 v[14:15], v[152:153], 0, s[4:5]
	v_lshlrev_b64 v[0:1], 11, v[0:1]
	v_ashrrev_i32_e32 v13, 31, v12
	v_mad_u64_u32 v[24:25], s[18:19], v14, s87, v[52:53]
	v_lshl_add_u64 v[0:1], s[6:7], 0, v[0:1]
	v_lshlrev_b32_e32 v48, 1, v2
	v_mad_i32_i24 v25, v15, s87, v25
	v_lshlrev_b64 v[54:55], 1, v[12:13]
	v_ashrrev_i32_e32 v155, 31, v154
	v_lshl_add_u64 v[0:1], v[0:1], 0, v[48:49]
	v_lshl_add_u64 v[4:5], v[156:157], 0, s[4:5]
	v_lshl_add_u64 v[12:13], v[24:25], 0, v[54:55]
	v_lshl_add_u64 v[24:25], v[154:155], 0, s[4:5]
	global_load_dwordx4 v[0:3], v[0:1], off
	v_lshlrev_b64 v[4:5], 11, v[4:5]
	v_ashrrev_i32_e32 v17, 31, v16
	v_mad_u64_u32 v[26:27], s[18:19], v24, s87, v[52:53]
	v_lshl_add_u64 v[4:5], s[6:7], 0, v[4:5]
	v_mad_i32_i24 v27, v25, s87, v27
	v_lshlrev_b64 v[56:57], 1, v[16:17]
	v_lshl_add_u64 v[4:5], v[4:5], 0, v[48:49]
	v_lshl_add_u64 v[16:17], v[26:27], 0, v[56:57]
	global_load_dwordx4 v[4:7], v[4:5], off
	v_add_u32_e32 v182, 0, v19
	global_load_dwordx4 v[8:11], v[8:9], off
	v_and_b32_e32 v72, 0x70, v18
	global_load_dwordx4 v[12:15], v[12:13], off
	v_add_u32_e32 v183, 0, v20
	global_load_dwordx4 v[24:27], v[16:17], off
	s_waitcnt vmcnt(0)
	v_add_u32_e32 v184, 0, v21
	v_add_u32_e32 v185, 0, v22
	v_add_u32_e32 v186, 0, v23
	v_bitop3_b32 v60, v65, v59, v72 bitop3:0xde
	v_add_u32_e32 v189, 0, v60
	s_movk_i32 s5, 0x80
	s_mov_b32 s44, s45
	v_add_u32_e32 v172, s16, v58
	v_lshl_add_u64 v[160:161], s[6:7], 0, v[48:49]
	v_lshl_add_u64 v[162:163], s[2:3], 0, v[50:51]
	v_lshl_add_u64 v[164:165], s[2:3], 0, v[54:55]
	v_lshl_add_u64 v[166:167], s[2:3], 0, v[56:57]
	v_cmp_gt_u32_e64 s[2:3], 32, v66
	s_waitcnt vmcnt(4)
	ds_write_b128 v182, v[0:3]
	v_mov_b32_e32 v0, 0x3000
	v_mad_u32_u24 v71, v168, s89, v0
	v_bitop3_b32 v0, v176, v59, v72 bitop3:0xde
	v_add_u32_e32 v187, 0, v0
	v_bitop3_b32 v67, v65, v71, v72 bitop3:0xde
	v_bitop3_b32 v64, v176, v71, v72 bitop3:0xde
	v_add_u32_e32 v202, 0, v64
	v_add_u32_e32 v201, 0, v67
	s_waitcnt vmcnt(3)
	ds_write_b128 v183, v[4:7]
	s_waitcnt vmcnt(2)
	ds_write_b128 v184, v[8:11] offset:32768
	s_waitcnt vmcnt(1)
	ds_write_b128 v185, v[12:15] offset:32768
	v_mov_b64_e32 v[0:1], s[44:45]
	s_waitcnt vmcnt(0)
	ds_write_b128 v186, v[24:27] offset:32768
	s_waitcnt lgkmcnt(0)
	s_barrier
	ds_read_b128 v[16:19], v187 offset:32768
	ds_read_b128 v[20:23], v187 offset:45056
	ds_read_b128 v[60:63], v189 offset:32768
	ds_read_b128 v[74:77], v189 offset:45056
	s_waitcnt lgkmcnt(3)
	v_mfma_f32_32x32x16_bf16 v[32:47], v[16:19], v[96:99], 0
	v_mov_b64_e32 v[14:15], s[58:59]
	v_mov_b64_e32 v[2:3], s[46:47]
	v_mov_b64_e32 v[4:5], s[48:49]
	v_mov_b64_e32 v[6:7], s[50:51]
	v_mov_b64_e32 v[8:9], s[52:53]
	v_mov_b64_e32 v[10:11], s[54:55]
	v_mov_b64_e32 v[12:13], s[56:57]
	s_waitcnt lgkmcnt(2)
	v_mfma_f32_32x32x16_bf16 v[16:31], v[20:23], v[96:99], 0
	s_waitcnt lgkmcnt(1)
	v_mfma_f32_32x32x16_bf16 v[32:47], v[60:63], v[100:103], v[32:47]
	v_or_b32_e32 v60, 64, v176
	v_bitop3_b32 v61, v60, v59, v72 bitop3:0xde
	v_add_u32_e32 v190, 0, v61
	ds_read_b128 v[78:81], v190 offset:45056
	v_bitop3_b32 v61, v60, v71, v72 bitop3:0xde
	v_or_b32_e32 v60, 0x60, v176
	v_bitop3_b32 v59, v60, v59, v72 bitop3:0xde
	s_waitcnt lgkmcnt(1)
	v_mfma_f32_32x32x16_bf16 v[16:31], v[74:77], v[100:103], v[16:31]
	ds_read_b128 v[74:77], v190 offset:32768
	v_add_u32_e32 v191, 0, v59
	v_bitop3_b32 v59, v60, v71, v72 bitop3:0xde
	v_bitop3_b32 v60, v176, v72, s5 bitop3:0x36
	v_mad_u32_u24 v62, v168, s89, v60
	v_add_u32_e32 v192, 0, v62
	s_movk_i32 s5, 0xa0
	s_waitcnt lgkmcnt(0)
	v_mfma_f32_32x32x16_bf16 v[32:47], v[74:77], v[104:107], v[32:47]
	ds_read_b128 v[74:77], v191 offset:32768
	v_bitop3_b32 v62, v176, v72, s5 bitop3:0x36
	v_mad_u32_u24 v63, v168, s89, v62
	v_add_u32_e32 v193, 0, v63
	s_movk_i32 s5, 0xc0
	v_bitop3_b32 v63, v176, v72, s5 bitop3:0x36
	v_mad_u32_u24 v65, v168, s89, v63
	v_mfma_f32_32x32x16_bf16 v[16:31], v[78:81], v[104:107], v[16:31]
	ds_read_b128 v[78:81], v191 offset:45056
	v_add_u32_e32 v194, 0, v65
	s_movk_i32 s5, 0xe0
	v_bitop3_b32 v65, v176, v72, s5 bitop3:0x36
	v_mad_u32_u24 v68, v168, s89, v65
	v_add_u32_e32 v195, 0, v68
	s_movk_i32 s5, 0x100
	s_waitcnt lgkmcnt(1)
	v_mfma_f32_32x32x16_bf16 v[32:47], v[74:77], v[108:111], v[32:47]
	ds_read_b128 v[74:77], v192 offset:32768
	v_bitop3_b32 v68, v176, v72, s5 bitop3:0x36
	v_mad_u32_u24 v69, v168, s89, v68
	v_add_u32_e32 v196, 0, v69
	s_movk_i32 s5, 0x120
	v_bitop3_b32 v69, v176, v72, s5 bitop3:0x36
	v_mad_u32_u24 v70, v168, s89, v69
	s_waitcnt lgkmcnt(1)
	v_mfma_f32_32x32x16_bf16 v[16:31], v[78:81], v[108:111], v[16:31]
	ds_read_b128 v[78:81], v192 offset:45056
	v_add_u32_e32 v197, 0, v70
	s_movk_i32 s5, 0x140
	v_bitop3_b32 v70, v176, v72, s5 bitop3:0x36
	v_mad_u32_u24 v73, v168, s89, v70
	v_add_u32_e32 v199, 0, v73
	s_movk_i32 s5, 0x160
	s_waitcnt lgkmcnt(1)
	v_mfma_f32_32x32x16_bf16 v[32:47], v[74:77], v[112:115], v[32:47]
	ds_read_b128 v[74:77], v193 offset:32768
	v_add_u32_e32 v60, v60, v71
	v_add_u32_e32 v62, v62, v71
	v_add_u32_e32 v63, v63, v71
	v_add_u32_e32 v65, v65, v71
	v_add_u32_e32 v68, v68, v71
	v_add_u32_e32 v69, v69, v71
	s_waitcnt lgkmcnt(1)
	v_mfma_f32_32x32x16_bf16 v[16:31], v[78:81], v[112:115], v[16:31]
	ds_read_b128 v[78:81], v193 offset:45056
	v_add_u32_e32 v70, v70, v71
	v_add_u32_e32 v209, 0, v61
	v_add_u32_e32 v212, 0, v59
	v_add_u32_e32 v211, 0, v60
	v_add_u32_e32 v210, 0, v62
	v_add_u32_e32 v208, 0, v63
	s_waitcnt lgkmcnt(1)
	v_mfma_f32_32x32x16_bf16 v[32:47], v[74:77], v[116:119], v[32:47]
	ds_read_b128 v[74:77], v194 offset:32768
	v_add_u32_e32 v207, 0, v65
	v_add_u32_e32 v206, 0, v68
	v_add_u32_e32 v205, 0, v69
	v_add_u32_e32 v204, 0, v70
	s_waitcnt lgkmcnt(1)
	v_mfma_f32_32x32x16_bf16 v[16:31], v[78:81], v[116:119], v[16:31]
	ds_read_b128 v[78:81], v194 offset:45056
	ds_read_b128 v[82:85], v171
	s_waitcnt lgkmcnt(0)
	v_mfma_f32_32x32x16_bf16 v[32:47], v[74:77], v[82:85], v[32:47]
	ds_read_b128 v[74:77], v195 offset:32768
	v_mfma_f32_32x32x16_bf16 v[16:31], v[78:81], v[82:85], v[16:31]
	ds_read_b128 v[78:81], v195 offset:45056
	ds_read_b128 v[82:85], v171 offset:1024
	s_waitcnt lgkmcnt(0)
	v_mfma_f32_32x32x16_bf16 v[32:47], v[74:77], v[82:85], v[32:47]
	ds_read_b128 v[74:77], v196 offset:32768
	v_mfma_f32_32x32x16_bf16 v[16:31], v[78:81], v[82:85], v[16:31]
	ds_read_b128 v[78:81], v196 offset:45056
	ds_read_b128 v[82:85], v171 offset:2048
	s_waitcnt lgkmcnt(0)
	v_mfma_f32_32x32x16_bf16 v[32:47], v[74:77], v[82:85], v[32:47]
	ds_read_b128 v[74:77], v197 offset:32768
	v_mfma_f32_32x32x16_bf16 v[16:31], v[78:81], v[82:85], v[16:31]
	ds_read_b128 v[78:81], v197 offset:45056
	ds_read_b128 v[82:85], v171 offset:3072
	s_waitcnt lgkmcnt(0)
	v_mfma_f32_32x32x16_bf16 v[32:47], v[74:77], v[82:85], v[32:47]
	ds_read_b128 v[74:77], v199 offset:32768
	v_mfma_f32_32x32x16_bf16 v[16:31], v[78:81], v[82:85], v[16:31]
	ds_read_b128 v[78:81], v199 offset:45056
	ds_read_b128 v[82:85], v171 offset:4096
	s_waitcnt lgkmcnt(0)
	v_mfma_f32_32x32x16_bf16 v[32:47], v[74:77], v[82:85], v[32:47]
	v_bitop3_b32 v76, v176, v72, s5 bitop3:0x36
	v_mad_u32_u24 v72, v168, s89, v76
	v_add_u32_e32 v198, 0, v72
	ds_read_b128 v[72:75], v198 offset:32768
	v_add_u32_e32 v71, v76, v71
	v_add_u32_e32 v203, 0, v71
	v_mfma_f32_32x32x16_bf16 v[16:31], v[78:81], v[82:85], v[16:31]
	ds_read_b128 v[76:79], v198 offset:45056
	ds_read_b128 v[80:83], v171 offset:5120
	s_waitcnt lgkmcnt(0)
	v_mfma_f32_32x32x16_bf16 v[32:47], v[72:75], v[80:83], v[32:47]
	v_mov_b32_e32 v74, 0xf149f2ca
	v_mfma_f32_32x32x16_bf16 v[16:31], v[76:79], v[80:83], v[16:31]
	s_nop 9
	v_max_f32_e32 v72, v33, v33
	v_max_f32_e32 v73, v32, v32
	v_max_f32_e32 v72, v73, v72
	v_max3_f32 v72, v72, v34, v35
	v_max3_f32 v72, v72, v36, v37
	v_max3_f32 v72, v72, v38, v39
	v_max3_f32 v72, v72, v40, v41
	v_max3_f32 v72, v72, v42, v43
	v_max3_f32 v72, v72, v44, v45
	v_max3_f32 v72, v72, v46, v47
	v_max3_f32 v72, v72, v16, v17
	v_max3_f32 v72, v72, v18, v19
	v_max3_f32 v72, v72, v20, v21
	v_max3_f32 v72, v72, v22, v23
	v_max3_f32 v72, v72, v24, v25
	v_max3_f32 v72, v72, v26, v27
	v_max3_f32 v72, v72, v28, v29
	v_max3_f32 v72, v72, v30, v31
	v_mov_b32_e32 v73, v72
	s_nop 1
	v_permlane32_swap_b32_e32 v72, v73
	v_max_f32_e32 v73, v73, v73
	v_max_f32_e32 v72, v72, v72
	v_max_f32_e32 v72, v72, v73
	v_add_f32_e32 v73, 0x7149f2ca, v72
	v_cmp_ge_f32_e32 vcc, s90, v73
	s_cmp_eq_u64 vcc, exec
	s_cselect_b64 vcc, -1, 0
	v_max_f32_e32 v72, 0xf149f2ca, v72
	s_add_i32 s18, s15, 0x8040
	v_cndmask_b32_e32 v158, v72, v74, vcc
	s_ashr_i32 s19, s18, 31
	v_sub_f32_e32 v132, v16, v158
	v_sub_f32_e32 v133, v17, v158
	v_lshl_add_u64 v[16:17], v[148:149], 0, s[18:19]
	v_sub_f32_e32 v124, v20, v158
	v_sub_f32_e32 v125, v21, v158
	v_lshlrev_b64 v[16:17], 11, v[16:17]
	v_lshl_add_u64 v[20:21], v[156:157], 0, s[18:19]
	v_sub_f32_e32 v128, v24, v158
	v_sub_f32_e32 v129, v25, v158
	v_lshl_add_u64 v[16:17], s[6:7], 0, v[16:17]
	v_lshlrev_b64 v[20:21], 11, v[20:21]
	v_lshl_add_u64 v[24:25], v[150:151], 0, s[18:19]
	v_sub_f32_e32 v32, v32, v158
	v_sub_f32_e32 v33, v33, v158
	v_sub_f32_e32 v130, v26, v158
	v_sub_f32_e32 v131, v27, v158
	v_sub_f32_e32 v120, v28, v158
	v_sub_f32_e32 v121, v29, v158
	v_lshl_add_u64 v[16:17], v[16:17], 0, v[48:49]
	v_lshl_add_u64 v[20:21], s[6:7], 0, v[20:21]
	v_mad_u64_u32 v[26:27], s[20:21], v24, s87, v[52:53]
	v_lshl_add_u64 v[28:29], v[152:153], 0, s[18:19]
	v_sub_f32_e32 v34, v34, v158
	v_sub_f32_e32 v35, v35, v158
	v_sub_f32_e32 v134, v18, v158
	v_sub_f32_e32 v135, v19, v158
	v_sub_f32_e32 v122, v30, v158
	v_sub_f32_e32 v123, v31, v158
	v_exp_f32_e32 v136, v32
	v_exp_f32_e32 v230, v33
	global_load_dwordx4 v[16:19], v[16:17], off
	v_lshl_add_u64 v[20:21], v[20:21], 0, v[48:49]
	v_mad_i32_i24 v27, v25, s87, v27
	v_mad_u64_u32 v[30:31], s[20:21], v28, s87, v[52:53]
	v_lshl_add_u64 v[32:33], v[154:155], 0, s[18:19]
	v_sub_f32_e32 v126, v22, v158
	v_sub_f32_e32 v127, v23, v158
	v_exp_f32_e32 v137, v34
	v_exp_f32_e32 v229, v35
	global_load_dwordx4 v[20:23], v[20:21], off
	v_lshl_add_u64 v[24:25], v[26:27], 0, v[50:51]
	v_mad_i32_i24 v31, v29, s87, v31
	v_mad_u64_u32 v[34:35], s[18:19], v32, s87, v[52:53]
	global_load_dwordx4 v[24:27], v[24:25], off
	v_lshl_add_u64 v[28:29], v[30:31], 0, v[54:55]
	v_mad_i32_i24 v35, v33, s87, v35
	global_load_dwordx4 v[28:31], v[28:29], off
	v_lshl_add_u64 v[32:33], v[34:35], 0, v[56:57]
	global_load_dwordx4 v[32:35], v[32:33], off
	v_sub_f32_e32 v73, 0xf149f2ca, v72
	v_exp_f32_e32 v73, v73
	v_sub_f32_e32 v36, v36, v158
	v_sub_f32_e32 v37, v37, v158
	v_sub_f32_e32 v38, v38, v158
	v_sub_f32_e32 v39, v39, v158
	v_sub_f32_e32 v40, v40, v158
	v_sub_f32_e32 v41, v41, v158
	v_sub_f32_e32 v42, v42, v158
	v_sub_f32_e32 v43, v43, v158
	v_sub_f32_e32 v44, v44, v158
	v_sub_f32_e32 v45, v45, v158
	v_sub_f32_e32 v46, v46, v158
	v_sub_f32_e32 v47, v47, v158
	v_exp_f32_e32 v138, v36
	v_exp_f32_e32 v228, v37
	v_exp_f32_e32 v139, v38
	v_exp_f32_e32 v213, v39
	v_exp_f32_e32 v144, v40
	v_exp_f32_e32 v147, v41
	v_exp_f32_e32 v145, v42
	v_exp_f32_e32 v146, v43
	v_exp_f32_e32 v141, v44
	v_exp_f32_e32 v143, v45
	v_exp_f32_e32 v140, v46
	v_exp_f32_e32 v142, v47
	s_waitcnt vmcnt(0)
	s_addk_i32 s16, 0x4000
	s_waitcnt vmcnt(4)
	ds_write_b128 v182, v[16:19] offset:16384
	s_waitcnt vmcnt(3)
	ds_write_b128 v183, v[20:23] offset:16384
	s_waitcnt vmcnt(2)
	ds_write_b128 v184, v[24:27] offset:57344
	s_waitcnt vmcnt(1)
	ds_write_b128 v185, v[28:31] offset:57344
	s_waitcnt vmcnt(0)
	ds_write_b128 v186, v[32:35] offset:57344
	v_add_u32_e32 v175, s16, v58
	v_mov_b64_e32 v[46:47], v[14:15]
	v_mov_b64_e32 v[30:31], v[14:15]
	v_mov_b64_e32 v[62:63], v[14:15]
	v_cndmask_b32_e64 v200, v73, 1.0, vcc
	s_add_i32 s15, s4, 0x80
	s_sub_i32 s14, s14, 64
	v_mov_b64_e32 v[44:45], v[12:13]
	v_mov_b64_e32 v[42:43], v[10:11]
	v_mov_b64_e32 v[40:41], v[8:9]
	v_mov_b64_e32 v[38:39], v[6:7]
	v_mov_b64_e32 v[36:37], v[4:5]
	v_mov_b64_e32 v[34:35], v[2:3]
	v_mov_b64_e32 v[32:33], v[0:1]
	v_mov_b64_e32 v[28:29], v[12:13]
	v_mov_b64_e32 v[26:27], v[10:11]
	v_mov_b64_e32 v[24:25], v[8:9]
	v_mov_b64_e32 v[22:23], v[6:7]
	v_mov_b64_e32 v[20:21], v[4:5]
	v_mov_b64_e32 v[18:19], v[2:3]
	v_mov_b64_e32 v[16:17], v[0:1]
	v_mov_b64_e32 v[60:61], v[12:13]
	v_mov_b64_e32 v[58:59], v[10:11]
	v_mov_b64_e32 v[56:57], v[8:9]
	v_mov_b64_e32 v[54:55], v[6:7]
	v_mov_b64_e32 v[52:53], v[4:5]
	v_mov_b64_e32 v[50:51], v[2:3]
	v_mov_b64_e32 v[48:49], v[0:1]
	s_waitcnt lgkmcnt(0)
	s_barrier
	v_lshlrev_b64 v[148:149], 11, v[148:149]
	v_lshlrev_b64 v[156:157], 11, v[156:157]
	v_lshl_add_u64 v[148:149], v[160:161], 0, v[148:149]
	v_lshl_add_u64 v[156:157], v[160:161], 0, v[156:157]
	v_mad_u64_u32 v[150:151], s[74:75], v150, s87, v[162:163]
	v_mad_u64_u32 v[152:153], s[74:75], v152, s87, v[164:165]
	v_mad_u64_u32 v[154:155], s[74:75], v154, s87, v[166:167]
	v_readfirstlane_b32 s21, v181
	s_nop 3
	s_lshr_b32 s21, s21, 6
	s_cmp_lt_u32 s21, 4
	s_cbranch_scc0 .Lattn_prio_done
	s_setprio 1
